# seam: census result and seam mode parked in v238 lanes after the first seam, later seams read them with v_readlane instead of two LDS round trips
# speedup vs baseline: 1.0077x; 1.0035x over previous
.Lxb_noinv:
	s_or_b64 exec, exec, s[4:5]
	v_cmp_eq_u32_e32 vcc, 0, v210
	s_and_saveexec_b64 s[4:5], vcc
	s_cbranch_execz .LBB0_463
	v_readlane_b32 s6, v240, 5
	v_readlane_b32 s7, v240, 6
	v_readlane_b32 s8, v240, 0
	s_add_i32 s101, s101, 1
	v_mov_b32_e32 v2, s101
	s_and_b32 s9, s8, 7
	s_lshl_b32 s9, s9, 8
	s_add_u32 s9, s9, 0x12000
	s_add_u32 s12, s6, s9
	s_addc_u32 s13, s7, 0
	s_lshr_b32 s9, s8, 3
	s_lshl_b32 s9, s9, 2
	v_mov_b32_e32 v3, s9
	global_store_dword v3, v2, s[12:13]
	s_and_b32 s3, s3, 15
	s_lshl_b32 s3, s3, 8
	s_cmp_eq_u32 s101, 1
	s_cbranch_scc1 .Lxb_first
	v_readlane_b32 s10, v238, 32
	v_readlane_b32 s11, v238, 33
	v_mov_b32_e32 v2, 1
	s_lshl_b32 s9, s8, 6
	s_add_u32 s9, s9, 0x4000
	s_add_u32 s14, s6, s9
	s_addc_u32 s15, s7, 0
	v_readlane_b32 s9, v238, 34
	s_branch .Lxb_have2
.Lxb_first:
	v_readlane_b32 s6, v240, 60
	s_nop 1
	v_mov_b32_e32 v0, s6
	ds_read_b64 v[0:1], v0
	v_readlane_b32 s6, v240, 5
	v_readlane_b32 s7, v240, 6
	s_waitcnt lgkmcnt(0)
	v_cmp_ne_u32_e32 vcc, 0, v0
	s_cbranch_vccnz .Lxb_have
	s_mov_b32 s12, 0

.Lxb_have:
	v_readfirstlane_b32 s10, v0
	v_readfirstlane_b32 s11, v1
	v_readlane_b32 s8, v240, 60
	v_mov_b32_e32 v2, 1
	s_nop 1
	v_mov_b32_e32 v4, s8
	ds_read_b32 v4, v4 offset:8
	v_readlane_b32 s8, v240, 0
	s_nop 0
	s_lshl_b32 s9, s8, 6
	s_add_u32 s9, s9, 0x4000
	s_add_u32 s14, s6, s9
	s_addc_u32 s15, s7, 0
	s_waitcnt lgkmcnt(0)
	v_readfirstlane_b32 s9, v4
	v_writelane_b32 v238, s10, 32
	v_writelane_b32 v238, s11, 33
	s_nop 1
	v_writelane_b32 v238, s9, 34
.Lxb_have2:
	s_cmp_eq_u32 s9, 1
	s_cbranch_scc0 .Lxb_grid
	s_mov_b32 s9, 0x3cfdf3f4
	s_bitcmp1_b32 s9, s70
	s_cbranch_scc0 .Lxb_grid
	s_and_b32 s9, s8, 7
	s_lshl_b32 s9, s9, 8
	s_add_u32 s9, s9, 0x12000
	s_add_u32 s12, s6, s9
	s_addc_u32 s13, s7, 0
	s_lshr_b32 s9, s8, 3
	s_lshl_b32 s9, s9, 2
	s_bfe_u32 s9, s8, 0x20003
	s_lshl_b32 s9, s9, 2
	s_mov_b32 exec_lo, 0xff
	s_mov_b32 exec_hi, 0
	v_mbcnt_lo_u32_b32 v3, -1, 0
	v_lshlrev_b32_e32 v3, 4, v3
	v_add_u32_e32 v3, s9, v3
	s_mov_b32 s9, 0
